# chain slimming (scalar-base DMA issue + o stores) plus gla_prep task-order rotation so first-written operand images are spread over all chains
# speedup vs baseline: 1.0133x; 1.0039x over previous
; #define PP_FETCH(task_) do { const int c_ = (task_) >> 2, h_ = (task_) & 3; const size_t t0_ = (size_t)c_ * 64; \
;         n_lr = *(const f32x4*)(LR + t0_ * 32 + tid * 4); \
;         _Pragma("unroll") for (int r_ = 0; r_ < 8; ++r_) { const bf16_t* rp_ = PG + (t0_ + rg * 8 + r_) * 2048 + h_ * 128 + c0; n_q[r_] = *(const unsigned*)rp_; n_k[r_] = *(const unsigned*)(rp_ + 512); } } while (0)
; DI void phase_gla_prep(const Params& P, int l, int bid, int nb, LAS unsigned char* lds) {
;     const int tid = threadIdx.x, wid = tid >> 6, lane = tid & 63, dpl = lane & 7, rg = lane >> 3, r32 = lane & 31, hi = lane >> 5;
;     const bf16_t* PG = (const bf16_t*)(P.ws + WS_PG); const float* LR = (const float*)(P.ws + WS_LR);
;     const int c0 = wid * 16 + dpl * 2;
;     const int p0 = (c0 & ~15) | (c0 & 3) | ((c0 & 4) << 1) | ((c0 & 8) >> 1);
;     int hcur = -1;
;     f32x4 n_lr; unsigned n_q[8], n_k[8];
;     ...
;     if (bid < 2560) PP_FETCH(bid);
;     f32x2 bbs[2] = {{0.f, 0.f}, {0.f, 0.f}};
;     for (int task = bid; task < 2560; task += nb) {
;     ...
;           for (int a4 = 0; a4 < 4; ++a4) { float v[4];
; #pragma unroll
;               for (int b4 = 0; b4 < 4; ++b4) { const int j = tj * 32 + 8 * a4 + 4 * hi + b4; const bool keep = dir ? (j >= i) : (j <= i); v[b4] = keep ? acc[a4 * 4 + b4] : 0.f; }
.LBB0_332:
	s_cmp_lt_i32 s72, 3
	s_cselect_b64 s[0:1], -1, 0
	s_cmp_gt_i32 s73, 2
	s_cselect_b64 s[2:3], -1, 0
	s_and_b64 s[0:1], s[0:1], s[2:3]
	s_andn2_b64 vcc, exec, s[0:1]
	s_cbranch_vccnz .LBB0_400
	s_cmpk_gt_i32 s33, 0x9ff
	v_and_b32_e32 v136, 0x3ff, v0
	s_cbranch_scc1 .LBB0_350
	s_mov_b32 s99, s33
	s_lshr_b32 s98, s33, 2
	s_mul_i32 s100, s98, 0xcccd
	s_lshr_b32 s100, s100, 19
	s_mul_i32 s100, s100, 10
	s_sub_i32 s98, s98, s100
	s_lshl_b32 s98, s98, 8
	s_add_i32 s33, s33, s98
	s_mov_b32 s101, s33
	v_lshrrev_b32_e32 v137, 6, v136
	v_and_b32_e32 v138, 7, v136
	v_lshlrev_b32_e32 v3, 2, v136
	v_lshlrev_b32_e32 v2, 4, v137
	v_and_or_b32 v4, v3, 8, v2
	v_lshlrev_b32_e32 v5, 1, v138
	v_and_b32_e32 v6, 4, v136
	v_bfe_u32 v9, v136, 3, 3
	v_and_or_b32 v6, v5, 2, v6
	v_lshrrev_b32_e32 v10, 3, v4
	v_bitop3_b32 v4, v9, v136, 7 bitop3:0x78
	s_add_u32 s74, s50, 0x10440000
	v_or_b32_e32 v8, v2, v5
	v_and_b32_e32 v5, 31, v136
	v_lshlrev_b32_e32 v11, 1, v6
	v_lshlrev_b32_e32 v32, 4, v4
	v_bfe_u32 v4, v136, 6, 1
	v_lshrrev_b32_e32 v6, 2, v136
	s_addc_u32 s75, s51, 0
	v_and_or_b32 v9, v6, 32, v5
	v_lshlrev_b32_e32 v6, 5, v4
	s_add_u32 s44, s50, 0x1f440000
	v_lshlrev_b32_e32 v2, 3, v5
	v_lshrrev_b32_e32 v12, 8, v136
	v_or_b32_e32 v5, v6, v5
	s_addc_u32 s45, s51, 0
	v_lshlrev_b32_e32 v13, 14, v12
	s_add_i32 s2, 0, 0x12000
	v_lshlrev_b32_e32 v5, 8, v5
	v_bfe_u32 v139, v136, 5, 1
	v_add3_u32 v140, s2, v13, v5
	v_lshlrev_b32_e32 v5, 8, v9
	v_add3_u32 v141, 0, v13, v5
	v_lshl_or_b32 v13, v139, 2, v6
	v_lshlrev_b32_e32 v6, 2, v8
	s_add_i32 s2, 0, 0x1a200
	v_add_u32_e32 v143, s2, v6
	s_add_i32 s2, 0, 0x1a400
	v_add_u32_e32 v144, s2, v6
	s_add_i32 s2, 0, 0x1a600
	v_add_u32_e32 v145, s2, v6
	s_add_i32 s2, 0, 0x1a800
	v_add_u32_e32 v146, s2, v6
	s_add_i32 s2, 0, 0x1aa00
	v_add_u32_e32 v147, s2, v6
	s_add_i32 s2, 0, 0x1ac00
	v_add_u32_e32 v148, s2, v6
	s_add_i32 s2, 0, 0x1ae00
	v_add_u32_e32 v149, s2, v6
	s_add_i32 s2, 0, 0x1b000
	v_add_u32_e32 v150, s2, v6
	s_add_i32 s2, 0, 0x1b200
	v_add_u32_e32 v151, s2, v6
	s_add_i32 s2, 0, 0x1b400
	v_add_u32_e32 v152, s2, v6
	s_add_i32 s2, 0, 0x1b600
	v_add_u32_e32 v153, s2, v6
	s_add_i32 s2, 0, 0x1b800
	v_add_u32_e32 v154, s2, v6
	s_add_i32 s2, 0, 0x1ba00
	v_add_u32_e32 v155, s2, v6
	s_add_i32 s2, 0, 0x1bc00
	v_and_b32_e32 v7, 63, v136
	v_and_b32_e32 v64, 56, v136
	v_add_u32_e32 v156, s2, v6
	s_add_i32 s2, 0, 0x1be00
	v_lshlrev_b32_e32 v24, 1, v8
	v_lshlrev_b32_e32 v30, 7, v8
	v_cmp_gt_u32_e64 s[0:1], 8, v7
	v_add_u32_e32 v157, s2, v6
	v_cmp_gt_u32_e64 s[2:3], 56, v7
	v_cmp_gt_u32_e64 s[4:5], 48, v7
	v_cmp_gt_u32_e64 s[6:7], 32, v7
	v_cmp_gt_u32_e64 s[8:9], 16, v7
	v_bitop3_b32 v7, v10, v136, 8 bitop3:0x78
	v_lshl_or_b32 v8, v64, 8, v11
	v_lshl_add_u32 v158, v7, 4, v8
	v_or_b32_e32 v7, 1, v64
	v_bitop3_b32 v8, v10, v7, 9 bitop3:0x78
	v_lshl_or_b32 v7, v7, 8, v11
	v_lshl_add_u32 v159, v8, 4, v7
	v_or_b32_e32 v7, 2, v64
	v_bitop3_b32 v8, v10, v7, 10 bitop3:0x78
	v_lshl_or_b32 v7, v7, 8, v11
	v_lshl_add_u32 v160, v8, 4, v7
	v_or_b32_e32 v7, 3, v64
	v_bitop3_b32 v8, v10, v7, 11 bitop3:0x78
	v_lshl_or_b32 v7, v7, 8, v11
	v_lshl_add_u32 v161, v8, 4, v7
	v_or_b32_e32 v7, 4, v64
	v_bitop3_b32 v8, v10, v7, 12 bitop3:0x78
	v_lshl_or_b32 v7, v7, 8, v11
	v_lshl_add_u32 v162, v8, 4, v7
	v_or_b32_e32 v7, 5, v64
	v_bitop3_b32 v8, v10, v7, 13 bitop3:0x78
	v_lshl_or_b32 v7, v7, 8, v11
	v_lshl_add_u32 v163, v8, 4, v7
	v_or_b32_e32 v7, 6, v64
	v_bitop3_b32 v8, v10, v7, 14 bitop3:0x78
	v_lshl_or_b32 v7, v7, 8, v11
	v_lshl_add_u32 v164, v8, 4, v7
	v_or_b32_e32 v7, 7, v64
	v_bitop3_b32 v8, v10, v7, 15 bitop3:0x78
	v_lshl_or_b32 v7, v7, 8, v11
	v_and_b32_e32 v14, 15, v136
	v_lshl_add_u32 v165, v8, 4, v7
	v_bitop3_b32 v7, v139, v136, 15 bitop3:0x78
	v_lshlrev_b32_e32 v166, 4, v7
	v_bitop3_b32 v7, v139, v14, 2 bitop3:0x36
	v_lshlrev_b32_e32 v167, 4, v7
	v_bitop3_b32 v7, v139, v14, 4 bitop3:0x36
	v_lshlrev_b32_e32 v168, 4, v7
	v_bitop3_b32 v7, v139, v14, 6 bitop3:0x36
	v_lshlrev_b32_e32 v169, 4, v7
	v_bitop3_b32 v7, v139, v14, 8 bitop3:0x36
	v_lshlrev_b32_e32 v170, 4, v7
	v_bitop3_b32 v7, v139, v14, 10 bitop3:0x36
	v_lshlrev_b32_e32 v171, 4, v7
	v_bitop3_b32 v7, v139, v14, 12 bitop3:0x36
	v_lshlrev_b32_e32 v172, 4, v7
	v_bitop3_b32 v7, v139, v14, 14 bitop3:0x36
	v_cmp_le_u32_e32 vcc, v13, v9
	s_movk_i32 s10, 0x100
	v_lshlrev_b32_e32 v173, 4, v7
	v_cndmask_b32_e64 v7, 0, 1, vcc
	v_cmp_ge_u32_e32 vcc, v13, v9
	v_cmp_lt_u32_e64 s[12:13], v13, v9
	v_lshlrev_b32_e32 v15, 2, v4
	v_cndmask_b32_e64 v8, 0, 1, vcc
	v_cmp_gt_u32_e32 vcc, s10, v136
	v_lshrrev_b32_e32 v65, 1, v136
	v_lshlrev_b32_e32 v17, 3, v139
	v_cndmask_b32_e32 v7, v8, v7, vcc
	v_and_b32_e32 v7, 1, v7
	v_cmp_eq_u32_e64 s[10:11], 1, v7
	v_or_b32_e32 v7, 1, v13
	v_cndmask_b32_e64 v8, 0, 1, s[12:13]
	v_cmp_ge_u32_e64 s[12:13], v7, v9
	v_bfe_u32 v16, v136, 1, 3
	v_add_u32_e32 v76, 0x200, v136
	v_cndmask_b32_e64 v7, 0, 1, s[12:13]
	v_cndmask_b32_e32 v7, v7, v8, vcc
	v_and_b32_e32 v7, 1, v7
	v_cmp_eq_u32_e64 s[12:13], 1, v7
	v_or_b32_e32 v7, 2, v13
	v_cmp_le_u32_e64 s[14:15], v7, v9
	s_add_i32 s70, 0, 0x1a000
	v_add_u32_e32 v81, 0x600, v136
	v_cndmask_b32_e64 v8, 0, 1, s[14:15]
	v_cmp_ge_u32_e64 s[14:15], v7, v9
	s_add_u32 s78, s50, 0x29e70000
	s_addc_u32 s79, s51, 0
	v_cndmask_b32_e64 v7, 0, 1, s[14:15]
	v_cndmask_b32_e32 v7, v7, v8, vcc
	v_and_b32_e32 v7, 1, v7
	v_cmp_eq_u32_e64 s[14:15], 1, v7
	v_or_b32_e32 v7, 3, v13
	v_cmp_le_u32_e64 s[16:17], v7, v9
	s_lshl_b32 s76, s33, 8
	s_and_b32 s76, s76, 0x300
	v_cndmask_b32_e64 v8, 0, 1, s[16:17]
	v_cmp_ge_u32_e64 s[16:17], v7, v9
	s_add_u32 s80, s74, s76
	v_mov_b32_e32 v25, 0
	v_cndmask_b32_e64 v7, 0, 1, s[16:17]
	v_cndmask_b32_e32 v7, v7, v8, vcc
; DI unsigned pkbf(float a, float b) { f32x2 v = {a, b}; bfx2 r = __builtin_convertvector(v, bfx2); return __builtin_bit_cast(unsigned, r); }
; DI void phase_gla_prep(const Params& P, int l, int bid, int nb, LAS unsigned char* lds) {
;     const int tid = threadIdx.x, wid = tid >> 6, lane = tid & 63, dpl = lane & 7, rg = lane >> 3, r32 = lane & 31, hi = lane >> 5;
;     const bf16_t* PG = (const bf16_t*)(P.ws + WS_PG); const float* LR = (const float*)(P.ws + WS_LR);
;     const int c0 = wid * 16 + dpl * 2;
;     const int p0 = (c0 & ~15) | (c0 & 3) | ((c0 & 4) << 1) | ((c0 & 8) >> 1);
;     ...
;           for (int a4 = 0; a4 < 4; ++a4) { float v[4];
; #pragma unroll
;               for (int b4 = 0; b4 < 4; ++b4) { const int j = tj * 32 + 8 * a4 + 4 * hi + b4; const bool keep = dir ? (j >= i) : (j <= i); v[b4] = keep ? acc[a4 * 4 + b4] : 0.f; }
;               u32x2 w; w.x = pkbf(v[0], v[1]); w.y = pkbf(v[2], v[3]);
;               *(u32x2*)(am + i * 128 + ((((4 * tj + a4) ^ ((i >> 1) & 7)) << 4) | (hi << 3))) = w; } }
	v_and_b32_e32 v7, 1, v7
	v_cmp_eq_u32_e64 s[16:17], 1, v7
	v_bitop3_b32 v7, v15, v65, 7 bitop3:0x78
	v_lshl_or_b32 v38, v7, 4, v17
	v_or_b32_e32 v7, 8, v13
	v_cmp_le_u32_e64 s[18:19], v7, v9
	s_addc_u32 s81, s75, 0
	v_mul_u32_u24_e32 v34, 0xa00, v12
	v_cndmask_b32_e64 v8, 0, 1, s[18:19]
	v_cmp_ge_u32_e64 s[18:19], v7, v9
	v_lshlrev_b32_e32 v83, 12, v12
	v_lshlrev_b32_e32 v56, 12, v64
	v_cndmask_b32_e64 v7, 0, 1, s[18:19]
	v_cndmask_b32_e32 v7, v7, v8, vcc
	v_and_b32_e32 v7, 1, v7
	v_cmp_eq_u32_e64 s[18:19], 1, v7
	v_or_b32_e32 v7, 9, v13
	v_cmp_le_u32_e64 s[20:21], v7, v9
	v_mov_b32_e32 v57, v25
	s_movk_i32 s76, 0x1000
	v_cndmask_b32_e64 v8, 0, 1, s[20:21]
	v_cmp_ge_u32_e64 s[20:21], v7, v9
	v_lshlrev_b32_e32 v22, 4, v136
	v_mov_b32_e32 v23, v25
	v_cndmask_b32_e64 v7, 0, 1, s[20:21]
	v_cndmask_b32_e32 v7, v7, v8, vcc
	v_and_b32_e32 v7, 1, v7
	v_cmp_eq_u32_e64 s[20:21], 1, v7
	v_or_b32_e32 v7, 10, v13
	v_cmp_le_u32_e64 s[22:23], v7, v9
	v_lshl_add_u64 v[26:27], s[44:45], 0, v[22:23]
	v_and_b32_e32 v4, 0xff, v136
	v_cndmask_b32_e64 v8, 0, 1, s[22:23]
	v_cmp_ge_u32_e64 s[22:23], v7, v9
	v_add_u32_e32 v142, s70, v6
	v_lshl_add_u32 v79, v4, 1, 0
	v_cndmask_b32_e64 v7, 0, 1, s[22:23]
	v_cndmask_b32_e32 v7, v7, v8, vcc
	v_and_b32_e32 v7, 1, v7
	v_cmp_eq_u32_e64 s[22:23], 1, v7
	v_or_b32_e32 v7, 11, v13
	v_cmp_le_u32_e64 s[24:25], v7, v9
	v_lshlrev_b32_e32 v4, 7, v4
	v_mov_b32_e32 v5, v25
	v_cndmask_b32_e64 v8, 0, 1, s[24:25]
	v_cmp_ge_u32_e64 s[24:25], v7, v9
	v_lshl_add_u32 v175, v64, 7, 0
	v_lshl_add_u64 v[4:5], s[50:51], 0, v[4:5]
	v_cndmask_b32_e64 v7, 0, 1, s[24:25]
	v_cndmask_b32_e32 v7, v7, v8, vcc
	v_and_b32_e32 v7, 1, v7
	v_cmp_eq_u32_e64 s[24:25], 1, v7
	v_bitop3_b32 v7, v15, v16, 1 bitop3:0x36
	v_lshl_or_b32 v40, v7, 4, v17
	v_or_b32_e32 v7, 16, v13
	v_cmp_le_u32_e64 s[26:27], v7, v9
	v_and_b32_e32 v78, 0x7f, v136
	s_movk_i32 s71, 0x200
	v_cndmask_b32_e64 v8, 0, 1, s[26:27]
	v_cmp_ge_u32_e64 s[26:27], v7, v9
	v_lshl_add_u64 v[66:67], s[78:79], 0, v[22:23]
	v_add_u32_e32 v180, s70, v3
	v_cndmask_b32_e64 v7, 0, 1, s[26:27]
	v_cndmask_b32_e32 v7, v7, v8, vcc
	v_and_b32_e32 v7, 1, v7
	v_cmp_eq_u32_e64 s[26:27], 1, v7
	v_or_b32_e32 v7, 17, v13
	v_cmp_le_u32_e64 s[28:29], v7, v9
	v_lshlrev_b32_e32 v10, 4, v81
	v_lshl_add_u64 v[28:29], s[74:75], 0, v[24:25]
	v_cndmask_b32_e64 v8, 0, 1, s[28:29]
	v_cmp_ge_u32_e64 s[28:29], v7, v9
	v_lshlrev_b32_e32 v36, 7, v9
	v_and_b32_e32 v10, 0x3ff0, v10
	v_cndmask_b32_e64 v7, 0, 1, s[28:29]
	v_cndmask_b32_e32 v7, v7, v8, vcc
	v_and_b32_e32 v7, 1, v7
	v_cmp_eq_u32_e64 s[28:29], 1, v7
	v_or_b32_e32 v7, 18, v13
	v_cmp_le_u32_e64 s[30:31], v7, v9
	v_mov_b32_e32 v11, v25
	s_mov_b32 s77, 0
	v_cndmask_b32_e64 v8, 0, 1, s[30:31]
	v_cmp_ge_u32_e64 s[30:31], v7, v9
	v_mov_b32_e32 v31, v25
	v_mov_b32_e32 v33, v25
	v_cndmask_b32_e64 v7, 0, 1, s[30:31]
	v_cndmask_b32_e32 v7, v7, v8, vcc
	v_and_b32_e32 v7, 1, v7
	v_cmp_eq_u32_e64 s[30:31], 1, v7
	v_or_b32_e32 v7, 19, v13
	v_cmp_le_u32_e64 s[34:35], v7, v9
	v_mov_b32_e32 v35, v25
	v_mov_b32_e32 v37, v25
	v_cndmask_b32_e64 v8, 0, 1, s[34:35]
	v_cmp_ge_u32_e64 s[34:35], v7, v9
	v_mov_b32_e32 v39, v25
	v_mov_b32_e32 v41, v25
	v_cndmask_b32_e64 v7, 0, 1, s[34:35]
	v_cndmask_b32_e32 v7, v7, v8, vcc
	v_and_b32_e32 v7, 1, v7
	v_cmp_eq_u32_e64 s[34:35], 1, v7
	v_bitop3_b32 v7, v15, v16, 2 bitop3:0x36
	v_lshl_or_b32 v42, v7, 4, v17
	v_or_b32_e32 v7, 24, v13
	v_cmp_le_u32_e64 s[36:37], v7, v9
	v_mov_b32_e32 v43, v25
	v_mov_b32_e32 v45, v25
	v_cndmask_b32_e64 v8, 0, 1, s[36:37]
	v_cmp_ge_u32_e64 s[36:37], v7, v9
	v_mov_b32_e32 v47, v25
	v_mov_b32_e32 v49, v25
	v_cndmask_b32_e64 v7, 0, 1, s[36:37]
	v_cndmask_b32_e32 v7, v7, v8, vcc
	v_and_b32_e32 v7, 1, v7
	v_cmp_eq_u32_e64 s[36:37], 1, v7
	v_or_b32_e32 v7, 25, v13
	v_cmp_le_u32_e64 s[38:39], v7, v9
	v_mov_b32_e32 v51, v25
	v_mov_b32_e32 v53, v25
	v_cndmask_b32_e64 v8, 0, 1, s[38:39]
	v_cmp_ge_u32_e64 s[38:39], v7, v9
	v_mov_b32_e32 v55, v25
	v_lshl_add_u64 v[72:73], s[78:79], 0, v[10:11]
	v_cndmask_b32_e64 v7, 0, 1, s[38:39]
	v_cndmask_b32_e32 v7, v7, v8, vcc
	v_and_b32_e32 v7, 1, v7
	v_cmp_eq_u32_e64 s[38:39], 1, v7
	v_or_b32_e32 v7, 26, v13
	v_cmp_le_u32_e64 s[40:41], v7, v9
	s_mov_b32 s96, 0xbfb8aa3b
	s_mov_b32 s97, 0xa000
	v_cndmask_b32_e64 v8, 0, 1, s[40:41]
	v_cmp_ge_u32_e64 s[40:41], v7, v9
	v_add_u32_e32 v205, v79, v83
	v_mov_b32_e32 v212, 0xa000
	v_cndmask_b32_e64 v7, 0, 1, s[40:41]
	v_cndmask_b32_e32 v7, v7, v8, vcc
	v_and_b32_e32 v7, 1, v7
	v_cmp_eq_u32_e64 s[40:41], 1, v7
	v_or_b32_e32 v7, 27, v13
	v_cmp_le_u32_e64 s[42:43], v7, v9
	s_mov_b32 s84, s33
	s_nop 0
	v_cndmask_b32_e64 v8, 0, 1, s[42:43]
	v_cmp_ge_u32_e64 s[42:43], v7, v9
	v_mov_b32_e32 v9, v25
	s_nop 0
	v_cndmask_b32_e64 v7, 0, 1, s[42:43]
; #define PP_FETCH(task_) do { const int c_ = (task_) >> 2, h_ = (task_) & 3; const size_t t0_ = (size_t)c_ * 64; \
;         n_lr = *(const f32x4*)(LR + t0_ * 32 + tid * 4); \
;         _Pragma("unroll") for (int r_ = 0; r_ < 8; ++r_) { const bf16_t* rp_ = PG + (t0_ + rg * 8 + r_) * 2048 + h_ * 128 + c0; n_q[r_] = *(const unsigned*)rp_; n_k[r_] = *(const unsigned*)(rp_ + 512); } } while (0)
; DI void phase_gla_prep(const Params& P, int l, int bid, int nb, LAS unsigned char* lds) {
;     ...
;     if (bid < 2560) PP_FETCH(bid);
;     f32x2 bbs[2] = {{0.f, 0.f}, {0.f, 0.f}};
;     for (int task = bid; task < 2560; task += nb) {
	v_cndmask_b32_e32 v7, v7, v8, vcc
	v_and_b32_e32 v7, 1, v7
	v_cmp_eq_u32_e64 s[42:43], 1, v7
	v_bitop3_b32 v7, v15, v16, 3 bitop3:0x36
	v_lshl_or_b32 v44, v7, 4, v17
	v_lshrrev_b32_e32 v7, 10, v76
	v_lshl_add_u32 v80, v7, 14, 0
	v_mul_u32_u24_e32 v46, 0xa00, v7
	v_lshrrev_b32_e32 v7, 10, v81
	v_lshl_add_u32 v82, v7, 14, 0
	v_mul_u32_u24_e32 v48, 0xa00, v7
	v_bitop3_b32 v7, v65, v12, 7 bitop3:0x6c
	v_lshlrev_b32_e32 v50, 4, v7
	v_lshrrev_b32_e32 v7, 8, v76
	v_lshlrev_b32_e32 v84, 12, v7
	v_bitop3_b32 v7, v7, v65, 7 bitop3:0x78
	v_lshlrev_b32_e32 v52, 4, v7
	v_or_b32_e32 v7, 4, v12
	v_lshlrev_b32_e32 v85, 12, v7
	v_bitop3_b32 v7, v12, v16, 4 bitop3:0x36
	v_lshl_add_u64 v[12:13], s[80:81], 0, v[24:25]
	s_ashr_i32 s80, s33, 2
	s_ashr_i32 s81, s80, 31
	s_lshl_b64 s[82:83], s[80:81], 18
	v_lshl_add_u64 v[12:13], v[12:13], 0, s[82:83]
	v_lshl_add_u64 v[12:13], v[12:13], 0, v[56:57]
	s_lshl_b64 s[80:81], s[80:81], 13
	v_add_co_u32_e32 v14, vcc, s76, v12
	s_add_u32 s44, s44, s80
	s_nop 0
	v_addc_co_u32_e32 v15, vcc, 0, v13, vcc
	s_movk_i32 s76, 0x2000
	s_addc_u32 s45, s45, s81
	v_add_co_u32_e32 v16, vcc, s76, v12
	v_lshlrev_b32_e32 v54, 4, v7
	s_nop 0
	v_addc_co_u32_e32 v17, vcc, 0, v13, vcc
	global_load_dwordx4 v[18:21], v22, s[44:45]
	global_load_dword v174, v[16:17], off offset:-4096
	global_load_dword v176, v[16:17], off
	global_load_dword v177, v[16:17], off offset:1024
	s_movk_i32 s44, 0x3000
	v_add_co_u32_e32 v16, vcc, s44, v12
	s_movk_i32 s44, 0x4000
	s_nop 0
	v_addc_co_u32_e32 v17, vcc, 0, v13, vcc
	v_add_co_u32_e32 v58, vcc, s44, v12
	s_movk_i32 s44, 0x5000
	s_nop 0
	v_addc_co_u32_e32 v59, vcc, 0, v13, vcc
	v_add_co_u32_e32 v60, vcc, s44, v12
	s_movk_i32 s44, 0x6000
	s_nop 0
	v_addc_co_u32_e32 v61, vcc, 0, v13, vcc
	v_add_co_u32_e32 v62, vcc, s44, v12
	s_movk_i32 s44, 0x7000
	s_nop 0
	v_addc_co_u32_e32 v63, vcc, 0, v13, vcc
	global_load_dword v185, v[58:59], off offset:-4096
	global_load_dword v186, v[58:59], off
	global_load_dword v187, v[58:59], off offset:1024
	global_load_dword v193, v[62:63], off offset:-4096
	global_load_dword v199, v[62:63], off
	global_load_dword v200, v[62:63], off offset:1024
	v_add_co_u32_e32 v58, vcc, s44, v12
	v_lshrrev_b32_e32 v7, 8, v81
	s_nop 0
	v_addc_co_u32_e32 v59, vcc, 0, v13, vcc
	global_load_dword v178, v[12:13], off
	global_load_dword v179, v[12:13], off offset:1024
	global_load_dword v192, v[14:15], off offset:1024
	global_load_dword v196, v[16:17], off offset:1024
	global_load_dword v209, v[60:61], off offset:1024
	global_load_dword v213, v[58:59], off
	global_load_dword v214, v[58:59], off offset:1024
	v_lshlrev_b32_e32 v12, 12, v7
	v_bitop3_b32 v7, v7, v65, 7 bitop3:0x78
	v_lshlrev_b32_e32 v58, 4, v7
	v_mov_b32_e32 v7, v25
	v_lshl_add_u64 v[60:61], s[54:55], 0, v[6:7]
	v_lshl_add_u64 v[62:63], s[58:59], 0, v[6:7]
	v_lshl_add_u64 v[6:7], s[50:51], 0, v[6:7]
	s_mov_b64 s[44:45], 0x3b670000
	v_lshl_add_u64 v[64:65], v[6:7], 0, s[44:45]
	v_lshl_add_u64 v[6:7], s[50:51], 0, v[22:23]
	s_mov_b64 s[44:45], 0x30270000
	v_lshl_add_u64 v[70:71], v[6:7], 0, s[44:45]
	s_mov_b64 s[44:45], 0x36670000
	v_lshl_add_u64 v[74:75], v[4:5], 0, s[44:45]
	v_lshlrev_b32_e32 v4, 2, v76
	s_movk_i32 s76, 0x1e00
	v_and_or_b32 v181, v4, s76, v78
	v_add_u32_e32 v182, s70, v4
	v_or_b32_e32 v4, 0x1000, v3
	v_and_or_b32 v183, v4, s76, v78
	v_add_u32_e32 v184, s70, v4
	v_mov_b32_e32 v4, s57
	v_mov_b32_e32 v5, s53
	v_cmp_gt_u32_e32 vcc, s71, v136
	v_lshlrev_b32_e32 v8, 4, v76
	s_movk_i32 s44, 0xe00
	v_cndmask_b32_e32 v77, v4, v5, vcc
	v_mov_b32_e32 v4, s56
	v_mov_b32_e32 v5, s52
	v_cndmask_b32_e32 v76, v4, v5, vcc
	v_lshlrev_b32_e32 v4, 2, v81
	v_and_or_b32 v188, v4, s76, v78
	v_add_u32_e32 v189, s70, v4
	v_add_u32_e32 v4, 0x2800, v3
	v_and_or_b32 v190, v4, s76, v78
	v_add_u32_e32 v191, s70, v4
	v_or_b32_e32 v4, 0xc00, v136
	v_and_or_b32 v23, v3, s44, v78
	v_lshlrev_b32_e32 v5, 2, v4
	v_add_u32_e32 v3, 0x3800, v3
	v_and_or_b32 v194, v5, s76, v78
	v_and_or_b32 v197, v3, s76, v78
	v_lshlrev_b32_e32 v78, 1, v2
	v_mbcnt_lo_u32_b32 v2, -1, 0
	v_and_b32_e32 v8, 0x3ff0, v8
	v_mov_b32_e32 v24, v25
	v_mbcnt_hi_u32_b32 v210, -1, v2
	v_mov_b32_e32 v2, 0x80
	v_mov_b32_e32 v59, v25
	v_lshl_add_u64 v[68:69], s[78:79], 0, v[8:9]
	v_add_u32_e32 v195, s70, v5
	v_cmp_gt_u32_e64 s[44:45], s44, v4
	v_add_u32_e32 v198, s70, v3
	s_mov_b32 s70, -1
	s_mov_b64 s[78:79], 0x800
	s_mov_b64 s[80:81], 0x29e76000
	s_mov_b64 s[82:83], 0x29e74000
	v_add_u32_e32 v201, v80, v8
	v_add_u32_e32 v202, v82, v10
	v_add_u32_e32 v206, v79, v84
	v_add_u32_e32 v207, v79, v85
	v_add_u32_e32 v208, v79, v12
	v_lshl_or_b32 v211, v210, 2, v2
	v_mov_b64_e32 v[82:83], v[24:25]
	v_mov_b64_e32 v[80:81], v[24:25]
	s_branch .LBB0_336

; #define LAS __attribute__((address_space(3)))
; #define PP_FETCH(task_) do { const int c_ = (task_) >> 2, h_ = (task_) & 3; const size_t t0_ = (size_t)c_ * 64; \
;         n_lr = *(const f32x4*)(LR + t0_ * 32 + tid * 4); \
;         _Pragma("unroll") for (int r_ = 0; r_ < 8; ++r_) { const bf16_t* rp_ = PG + (t0_ + rg * 8 + r_) * 2048 + h_ * 128 + c0; n_q[r_] = *(const unsigned*)rp_; n_k[r_] = *(const unsigned*)(rp_ + 512); } } while (0)
; DI void phase_gla_prep(const Params& P, int l, int bid, int nb, LAS unsigned char* lds) {
;     ...
;         *(LAS f32x4*)(lds + PP_LR + tid * 16) = n_lr;
;         unsigned qw[8], kw[8];
; #pragma unroll
;         for (int r = 0; r < 8; ++r) { qw[r] = n_q[r]; kw[r] = n_k[r]; }
;         asm volatile("" : "+v"(qw[0]), "+v"(qw[1]), "+v"(qw[2]), "+v"(qw[3]), "+v"(qw[4]), "+v"(qw[5]), "+v"(qw[6]), "+v"(qw[7]), "+v"(kw[0]), "+v"(kw[1]), "+v"(kw[2]), "+v"(kw[3]), "+v"(kw[4]), "+v"(kw[5]), "+v"(kw[6]), "+v"(kw[7]) :: "memory");
;         __builtin_amdgcn_sched_barrier(0);
;         { const int wu = __builtin_amdgcn_readfirstlane(wid);
; #pragma unroll
;           for (int q = 0; q < 4; ++q) { const int row = wu * 8 + q * 2 + (lane >> 5);
;               __builtin_amdgcn_global_load_lds((const unsigned*)(PG + ((size_t)c * 64 + row) * 2048 + 1024 + h * 256 + (lane & 31) * 8), (LAS unsigned*)(lds + PP_V + (wu * 8 + q * 2) * 512), 16, 0, 0); } }
;         if (task + nb < 2560) PP_FETCH(task + nb);
.LBB0_340:
	v_add_u32_e32 v24, 0, v22
	ds_write_b128 v24, v[18:21]
	v_mov_b32_e32 v14, v179
	v_mov_b32_e32 v2, v214
	v_mov_b32_e32 v9, v185
	v_mov_b32_e32 v11, v177
	v_mov_b32_e32 v5, v193
	v_mov_b32_e32 v7, v187
	v_mov_b32_e32 v16, v178
	v_mov_b32_e32 v3, v213
	v_mov_b32_e32 v4, v200
	v_mov_b32_e32 v13, v176
	v_mov_b32_e32 v15, v192
	v_mov_b32_e32 v10, v186
	v_mov_b32_e32 v12, v196
	v_mov_b32_e32 v6, v199
	v_mov_b32_e32 v8, v209
	v_mov_b32_e32 v17, v174
	s_ashr_i32 s86, s84, 2
	v_readfirstlane_b32 s85, v137
	s_lshl_b32 s88, s85, 3
	s_ashr_i32 s87, s86, 31
	s_lshl_b64 s[86:87], s[86:87], 18
	v_or_b32_e32 v84, s88, v139
	s_add_u32 s86, s74, s86
	v_ashrrev_i32_e32 v85, 31, v84
	s_addc_u32 s87, s75, s87
	v_lshlrev_b64 v[84:85], 12, v[84:85]
	v_lshl_add_u64 v[84:85], s[86:87], 0, v[84:85]
	s_lshl_b32 s76, s71, 9
	v_lshl_add_u64 v[84:85], v[84:85], 0, s[76:77]
	v_mov_b32_e32 v79, v25
	s_lshl_b32 s71, s85, 12
	v_lshl_add_u64 v[84:85], v[84:85], 0, v[78:79]
	s_add_i32 s71, s71, 0
	v_lshl_add_u64 v[84:85], v[84:85], 0, s[78:79]
	s_add_i32 m0, s71, 0x2000
	s_or_b32 s71, s88, 2
	global_load_lds_dwordx4 v[84:85], off
	v_or_b32_e32 v84, s71, v139
	v_ashrrev_i32_e32 v85, 31, v84
	v_lshlrev_b64 v[84:85], 12, v[84:85]
	v_lshl_add_u64 v[84:85], s[86:87], 0, v[84:85]
	v_lshl_add_u64 v[84:85], v[84:85], 0, s[76:77]
	s_lshl_b32 s71, s71, 9
	v_lshl_add_u64 v[84:85], v[84:85], 0, v[78:79]
	s_add_i32 s71, s71, 0
	v_lshl_add_u64 v[84:85], v[84:85], 0, s[78:79]
	s_add_i32 m0, s71, 0x2000
	s_or_b32 s71, s88, 4
	global_load_lds_dwordx4 v[84:85], off
	v_or_b32_e32 v84, s71, v139
	v_ashrrev_i32_e32 v85, 31, v84
	v_lshlrev_b64 v[84:85], 12, v[84:85]
	v_lshl_add_u64 v[84:85], s[86:87], 0, v[84:85]
	v_lshl_add_u64 v[84:85], v[84:85], 0, s[76:77]
	s_lshl_b32 s71, s71, 9
	v_lshl_add_u64 v[84:85], v[84:85], 0, v[78:79]
	s_add_i32 s71, s71, 0
	v_lshl_add_u64 v[84:85], v[84:85], 0, s[78:79]
	s_add_i32 m0, s71, 0x2000
	s_or_b32 s71, s88, 6
	global_load_lds_dwordx4 v[84:85], off
	v_or_b32_e32 v84, s71, v139
	v_ashrrev_i32_e32 v85, 31, v84
	v_lshlrev_b64 v[84:85], 12, v[84:85]
	v_lshl_add_u64 v[84:85], s[86:87], 0, v[84:85]
	v_lshl_add_u64 v[84:85], v[84:85], 0, s[76:77]
	s_lshl_b32 s71, s71, 9
	v_lshl_add_u64 v[84:85], v[84:85], 0, v[78:79]
	s_add_i32 s71, s71, 0
	v_lshl_add_u64 v[84:85], v[84:85], 0, s[78:79]
	s_add_i32 m0, s71, 0x2000
	s_add_i32 s71, s84, s94
	global_load_lds_dwordx4 v[84:85], off
	s_cmpk_gt_i32 s71, 0x9ff
	s_cselect_b32 s98, 0xa00, 0
	s_sub_i32 s71, s71, s98
	s_cmp_eq_u32 s71, s101
	s_cselect_b64 s[86:87], -1, 0
	s_and_b64 vcc, exec, s[86:87]
	s_cbranch_vccnz .LBB0_342
	s_ashr_i32 s88, s71, 2
	s_lshl_b32 s76, s71, 8
	s_ashr_i32 s89, s88, 31
	s_and_b32 s76, s76, 0x300
	s_lshl_b64 s[90:91], s[88:89], 13
	v_lshl_add_u64 v[20:21], v[28:29], 0, s[76:77]
	s_lshl_b64 s[88:89], s[88:89], 18
	v_lshl_add_u64 v[20:21], v[20:21], 0, s[88:89]
	v_lshl_add_u64 v[84:85], v[20:21], 0, v[56:57]
	v_add_co_u32_e32 v86, vcc, 0x1000, v84
	v_lshl_add_u64 v[18:19], v[26:27], 0, s[90:91]
	s_nop 0
	v_addc_co_u32_e32 v87, vcc, 0, v85, vcc
	v_add_co_u32_e32 v88, vcc, 0x2000, v84
	global_load_dwordx4 v[18:21], v[18:19], off
	s_nop 0
	global_load_dword v178, v[84:85], off
	global_load_dword v179, v[84:85], off offset:1024
	global_load_dword v174, v[86:87], off
	v_addc_co_u32_e32 v89, vcc, 0, v85, vcc
	v_add_co_u32_e32 v90, vcc, 0x3000, v84
	s_nop 1
	v_addc_co_u32_e32 v91, vcc, 0, v85, vcc
	v_add_co_u32_e32 v92, vcc, 0x4000, v84
	s_nop 1
	v_addc_co_u32_e32 v93, vcc, 0, v85, vcc
	v_add_co_u32_e32 v94, vcc, 0x5000, v84
	s_nop 1
	v_addc_co_u32_e32 v95, vcc, 0, v85, vcc
	global_load_dword v192, v[86:87], off offset:1024
	global_load_dword v176, v[88:89], off
	global_load_dword v177, v[88:89], off offset:1024
	global_load_dword v185, v[90:91], off
	global_load_dword v196, v[90:91], off offset:1024
	global_load_dword v186, v[92:93], off
	global_load_dword v187, v[92:93], off offset:1024
	global_load_dword v193, v[94:95], off
	v_add_co_u32_e32 v86, vcc, 0x6000, v84
	s_nop 1
	v_addc_co_u32_e32 v87, vcc, 0, v85, vcc
	v_add_co_u32_e32 v84, vcc, 0x7000, v84
	s_nop 1
	v_addc_co_u32_e32 v85, vcc, 0, v85, vcc
	global_load_dword v209, v[94:95], off offset:1024
	global_load_dword v199, v[86:87], off
	global_load_dword v200, v[86:87], off offset:1024
	global_load_dword v213, v[84:85], off
	global_load_dword v214, v[84:85], off offset:1024

; __device__ __forceinline__ unsigned xb_ld(unsigned* p)              { return __hip_atomic_load(p, __ATOMIC_RELAXED, __HIP_MEMORY_SCOPE_AGENT); }
; __device__ __forceinline__ void xcd_barrier_complete(unsigned* bar, unsigned x, unsigned& nloc, unsigned& nx) {
;     const unsigned G = gridDim.x * gridDim.y * gridDim.z;
;     unsigned sum, cnt, mine, sp = 0u;
;     for (;;) {
;         sum = 0u; cnt = 0u; mine = 0u;
; #pragma unroll
;         for (unsigned j = 0; j < 16; ++j) { const unsigned c = xb_ld(&bar[XB_XCNT(j)]); sum += c; cnt += (c > 0u) ? 1u : 0u; mine = (j == x) ? c : mine; }
; __device__ __forceinline__ void xcd_barrier(const XcdBarrier& b) {
;     ...
;     if (threadIdx.x == 0) {
;         unsigned* bar = b.bar;
;         __builtin_amdgcn_s_waitcnt(0);
;         unsigned nloc = b.st[0], nx = b.st[1];
;         if (nloc == 0u) { xcd_barrier_complete(bar, b.x, nloc, nx); b.st[0] = nloc; b.st[1] = nx; }
.LBB0_350:
	s_mov_b32 s33, s99
	s_cmp_lt_i32 s73, 4
	s_cbranch_scc1 .LBB0_400
	s_waitcnt vmcnt(0)
	v_cmp_eq_u32_e32 vcc, 0, v136
	s_waitcnt vmcnt(0) lgkmcnt(0)
	s_barrier
	s_and_saveexec_b64 s[0:1], vcc
	s_cbranch_execz .LBB0_399
	s_add_i32 s2, 0, 0x26000
	v_mov_b32_e32 v2, s2
	s_waitcnt vmcnt(0) expcnt(0) lgkmcnt(0)
	ds_read_b32 v4, v2
	s_add_i32 s2, 0, 0x26004
	v_mov_b32_e32 v2, s2
	ds_read_b32 v2, v2
	s_waitcnt lgkmcnt(1)
	v_cmp_ne_u32_e32 vcc, 0, v4
	s_cbranch_vccnz .LBB0_367
	v_readlane_b32 s2, v254, 4
	v_readlane_b32 s3, v254, 5
	s_load_dwordx2 s[6:7], s[2:3], 0x4
	s_add_u32 s2, s50, 0x29e6c200
	s_addc_u32 s3, s51, 0
	s_add_u32 s4, s50, 0x29e6c400
	s_addc_u32 s5, s51, 0
	s_waitcnt lgkmcnt(0)
	s_mul_i32 s44, s6, s94
	s_add_u32 s6, s50, 0x29e6c500
	s_mul_i32 s44, s44, s7
	s_addc_u32 s7, s51, 0
	s_add_u32 s8, s50, 0x29e6c600
	s_addc_u32 s9, s51, 0
	s_add_u32 s10, s50, 0x29e6c700
	s_addc_u32 s11, s51, 0
	s_add_u32 s12, s50, 0x29e6c800
	s_addc_u32 s13, s51, 0
	s_add_u32 s14, s50, 0x29e6c900
	s_addc_u32 s15, s51, 0
	s_add_u32 s16, s50, 0x29e6ca00
	s_addc_u32 s17, s51, 0
	s_add_u32 s18, s50, 0x29e6cb00
	s_addc_u32 s19, s51, 0
	s_add_u32 s20, s50, 0x29e6cc00
	s_addc_u32 s21, s51, 0
	s_add_u32 s22, s50, 0x29e6cd00
	s_addc_u32 s23, s51, 0
	s_add_u32 s24, s50, 0x29e6ce00
	s_addc_u32 s25, s51, 0
	s_add_u32 s26, s50, 0x29e6cf00
	s_addc_u32 s27, s51, 0
	s_add_u32 s28, s50, 0x29e6d000
	s_addc_u32 s29, s51, 0
	s_add_u32 s30, s50, 0x29e6d100
	s_addc_u32 s31, s51, 0
	s_add_u32 s34, s50, 0x29e6d200
	s_addc_u32 s35, s51, 0
	s_add_u32 s36, s50, 0x29e6d300
	s_addc_u32 s37, s51, 0
	s_mov_b32 s45, 1
	v_mov_b32_e32 v18, 0
	s_branch .LBB0_355

; #define PP_FETCH(task_) do { const int c_ = (task_) >> 2, h_ = (task_) & 3; const size_t t0_ = (size_t)c_ * 64; \
;         n_lr = *(const f32x4*)(LR + t0_ * 32 + tid * 4); \
;         _Pragma("unroll") for (int r_ = 0; r_ < 8; ++r_) { const bf16_t* rp_ = PG + (t0_ + rg * 8 + r_) * 2048 + h_ * 128 + c0; n_q[r_] = *(const unsigned*)rp_; n_k[r_] = *(const unsigned*)(rp_ + 512); } } while (0)
; DI void phase_gla_prep(const Params& P, int l, int bid, int nb, LAS unsigned char* lds) {
;     const int tid = threadIdx.x, wid = tid >> 6, lane = tid & 63, dpl = lane & 7, rg = lane >> 3, r32 = lane & 31, hi = lane >> 5;
;     const bf16_t* PG = (const bf16_t*)(P.ws + WS_PG); const float* LR = (const float*)(P.ws + WS_LR);
;     const int c0 = wid * 16 + dpl * 2;
;     const int p0 = (c0 & ~15) | (c0 & 3) | ((c0 & 4) << 1) | ((c0 & 8) >> 1);
;     int hcur = -1;
;     f32x4 n_lr; unsigned n_q[8], n_k[8];
;     ...
;     if (bid < 2560) PP_FETCH(bid);
;     f32x2 bbs[2] = {{0.f, 0.f}, {0.f, 0.f}};
;     for (int task = bid; task < 2560; task += nb) {
;     ...
;           for (int a4 = 0; a4 < 4; ++a4) { float v[4];
; #pragma unroll
;               for (int b4 = 0; b4 < 4; ++b4) { const int j = tj * 32 + 8 * a4 + 4 * hi + b4; const bool keep = dir ? (j >= i) : (j <= i); v[b4] = keep ? acc[a4 * 4 + b4] : 0.f; }
.LBB0_894:
	s_cmp_lt_i32 s72, 9
	s_cselect_b64 s[0:1], -1, 0
	s_cmp_gt_i32 s73, 8
	s_cselect_b64 s[2:3], -1, 0
	s_and_b64 s[0:1], s[0:1], s[2:3]
	s_andn2_b64 vcc, exec, s[0:1]
	s_cbranch_vccnz .LBB0_962
	s_cmpk_gt_i32 s33, 0x9ff
	v_and_b32_e32 v136, 0x3ff, v0
	s_cbranch_scc1 .LBB0_912
	s_mov_b32 s99, s33
	s_lshr_b32 s98, s33, 2
	s_mul_i32 s100, s98, 0xcccd
	s_lshr_b32 s100, s100, 19
	s_mul_i32 s100, s100, 10
	s_sub_i32 s98, s98, s100
	s_lshl_b32 s98, s98, 8
	s_add_i32 s33, s33, s98
	s_mov_b32 s101, s33
	v_lshrrev_b32_e32 v137, 6, v136
	v_and_b32_e32 v138, 7, v136
	v_lshlrev_b32_e32 v3, 2, v136
	v_lshlrev_b32_e32 v2, 4, v137
	v_and_or_b32 v4, v3, 8, v2
	v_lshlrev_b32_e32 v5, 1, v138
	v_and_b32_e32 v6, 4, v136
	v_bfe_u32 v9, v136, 3, 3
	v_and_or_b32 v6, v5, 2, v6
	v_lshrrev_b32_e32 v10, 3, v4
	v_bitop3_b32 v4, v9, v136, 7 bitop3:0x78
	s_add_u32 s74, s50, 0x10440000
	v_or_b32_e32 v8, v2, v5
	v_and_b32_e32 v5, 31, v136
	v_lshlrev_b32_e32 v11, 1, v6
	v_lshlrev_b32_e32 v32, 4, v4
	v_bfe_u32 v4, v136, 6, 1
	v_lshrrev_b32_e32 v6, 2, v136
	s_addc_u32 s75, s51, 0
	v_and_or_b32 v9, v6, 32, v5
	v_lshlrev_b32_e32 v6, 5, v4
	s_add_u32 s44, s50, 0x1f440000
	v_lshlrev_b32_e32 v2, 3, v5
	v_lshrrev_b32_e32 v12, 8, v136
	v_or_b32_e32 v5, v6, v5
	s_addc_u32 s45, s51, 0
	v_lshlrev_b32_e32 v13, 14, v12
	s_add_i32 s2, 0, 0x12000
	v_lshlrev_b32_e32 v5, 8, v5
	v_bfe_u32 v139, v136, 5, 1
	v_add3_u32 v140, s2, v13, v5
	v_lshlrev_b32_e32 v5, 8, v9
	v_add3_u32 v141, 0, v13, v5
	v_lshl_or_b32 v13, v139, 2, v6
	v_lshlrev_b32_e32 v6, 2, v8
	s_add_i32 s2, 0, 0x1a200
	v_add_u32_e32 v143, s2, v6
	s_add_i32 s2, 0, 0x1a400
	v_add_u32_e32 v144, s2, v6
	s_add_i32 s2, 0, 0x1a600
	v_add_u32_e32 v145, s2, v6
	s_add_i32 s2, 0, 0x1a800
	v_add_u32_e32 v147, s2, v6
	s_add_i32 s2, 0, 0x1aa00
	v_add_u32_e32 v148, s2, v6
	s_add_i32 s2, 0, 0x1ac00
	v_add_u32_e32 v149, s2, v6
	s_add_i32 s2, 0, 0x1ae00
	v_add_u32_e32 v150, s2, v6
	s_add_i32 s2, 0, 0x1b000
	v_add_u32_e32 v151, s2, v6
	s_add_i32 s2, 0, 0x1b200
	v_add_u32_e32 v152, s2, v6
	s_add_i32 s2, 0, 0x1b400
	v_add_u32_e32 v153, s2, v6
	s_add_i32 s2, 0, 0x1b600
	v_add_u32_e32 v154, s2, v6
	s_add_i32 s2, 0, 0x1b800
	v_add_u32_e32 v155, s2, v6
	s_add_i32 s2, 0, 0x1ba00
	v_add_u32_e32 v156, s2, v6
	s_add_i32 s2, 0, 0x1bc00
	s_waitcnt lgkmcnt(0)
	v_and_b32_e32 v7, 63, v136
	v_and_b32_e32 v64, 56, v136
	v_add_u32_e32 v157, s2, v6
	s_add_i32 s2, 0, 0x1be00
	v_lshlrev_b32_e32 v24, 1, v8
	v_lshlrev_b32_e32 v30, 7, v8
	v_cmp_gt_u32_e64 s[0:1], 8, v7
	v_add_u32_e32 v158, s2, v6
	v_cmp_gt_u32_e64 s[2:3], 56, v7
	v_cmp_gt_u32_e64 s[4:5], 48, v7
	v_cmp_gt_u32_e64 s[6:7], 32, v7
	v_cmp_gt_u32_e64 s[8:9], 16, v7
	v_bitop3_b32 v7, v10, v136, 8 bitop3:0x78
	v_lshl_or_b32 v8, v64, 8, v11
	v_lshl_add_u32 v159, v7, 4, v8
	v_or_b32_e32 v7, 1, v64
	v_bitop3_b32 v8, v10, v7, 9 bitop3:0x78
	v_lshl_or_b32 v7, v7, 8, v11
	v_lshl_add_u32 v160, v8, 4, v7
	v_or_b32_e32 v7, 2, v64
	v_bitop3_b32 v8, v10, v7, 10 bitop3:0x78
	v_lshl_or_b32 v7, v7, 8, v11
	v_lshl_add_u32 v162, v8, 4, v7
	v_or_b32_e32 v7, 3, v64
	v_bitop3_b32 v8, v10, v7, 11 bitop3:0x78
	v_lshl_or_b32 v7, v7, 8, v11
	v_lshl_add_u32 v164, v8, 4, v7
	v_or_b32_e32 v7, 4, v64
	v_bitop3_b32 v8, v10, v7, 12 bitop3:0x78
	v_lshl_or_b32 v7, v7, 8, v11
	v_lshl_add_u32 v165, v8, 4, v7
	v_or_b32_e32 v7, 5, v64
	v_bitop3_b32 v8, v10, v7, 13 bitop3:0x78
	v_lshl_or_b32 v7, v7, 8, v11
	v_lshl_add_u32 v166, v8, 4, v7
	v_or_b32_e32 v7, 6, v64
	v_bitop3_b32 v8, v10, v7, 14 bitop3:0x78
	v_lshl_or_b32 v7, v7, 8, v11
	v_lshl_add_u32 v167, v8, 4, v7
	v_or_b32_e32 v7, 7, v64
	v_bitop3_b32 v8, v10, v7, 15 bitop3:0x78
	v_lshl_or_b32 v7, v7, 8, v11
	v_and_b32_e32 v14, 15, v136
	v_lshl_add_u32 v168, v8, 4, v7
	v_bitop3_b32 v7, v139, v136, 15 bitop3:0x78
	v_lshlrev_b32_e32 v169, 4, v7
	v_bitop3_b32 v7, v139, v14, 2 bitop3:0x36
	v_lshlrev_b32_e32 v170, 4, v7
	v_bitop3_b32 v7, v139, v14, 4 bitop3:0x36
	v_lshlrev_b32_e32 v171, 4, v7
	v_bitop3_b32 v7, v139, v14, 6 bitop3:0x36
	v_lshlrev_b32_e32 v172, 4, v7
	v_bitop3_b32 v7, v139, v14, 8 bitop3:0x36
	v_lshlrev_b32_e32 v173, 4, v7
	v_bitop3_b32 v7, v139, v14, 10 bitop3:0x36
	v_lshlrev_b32_e32 v174, 4, v7
	v_bitop3_b32 v7, v139, v14, 12 bitop3:0x36
	v_lshlrev_b32_e32 v175, 4, v7
	v_bitop3_b32 v7, v139, v14, 14 bitop3:0x36
	v_cmp_le_u32_e32 vcc, v13, v9
	s_movk_i32 s10, 0x100
	v_lshlrev_b32_e32 v176, 4, v7
	v_cndmask_b32_e64 v7, 0, 1, vcc
	v_cmp_ge_u32_e32 vcc, v13, v9
	v_cmp_lt_u32_e64 s[12:13], v13, v9
	v_lshlrev_b32_e32 v15, 2, v4
	v_cndmask_b32_e64 v8, 0, 1, vcc
	v_cmp_gt_u32_e32 vcc, s10, v136
	v_lshrrev_b32_e32 v65, 1, v136
	v_lshlrev_b32_e32 v17, 3, v139
	v_cndmask_b32_e32 v7, v8, v7, vcc
	v_and_b32_e32 v7, 1, v7
	v_cmp_eq_u32_e64 s[10:11], 1, v7
	v_or_b32_e32 v7, 1, v13
	v_cndmask_b32_e64 v8, 0, 1, s[12:13]
	v_cmp_ge_u32_e64 s[12:13], v7, v9
	v_bfe_u32 v16, v136, 1, 3
	v_add_u32_e32 v76, 0x200, v136
	v_cndmask_b32_e64 v7, 0, 1, s[12:13]
	v_cndmask_b32_e32 v7, v7, v8, vcc
	v_and_b32_e32 v7, 1, v7
	v_cmp_eq_u32_e64 s[12:13], 1, v7
	v_or_b32_e32 v7, 2, v13
	v_cmp_le_u32_e64 s[14:15], v7, v9
	s_add_i32 s70, 0, 0x1a000
	v_add_u32_e32 v81, 0x600, v136
	v_cndmask_b32_e64 v8, 0, 1, s[14:15]
	v_cmp_ge_u32_e64 s[14:15], v7, v9
	s_add_u32 s78, s50, 0x29e70000
	s_addc_u32 s79, s51, 0
	v_cndmask_b32_e64 v7, 0, 1, s[14:15]
	v_cndmask_b32_e32 v7, v7, v8, vcc
	v_and_b32_e32 v7, 1, v7
	v_cmp_eq_u32_e64 s[14:15], 1, v7
	v_or_b32_e32 v7, 3, v13
	v_cmp_le_u32_e64 s[16:17], v7, v9
	s_lshl_b32 s65, s33, 8
	s_and_b32 s65, s65, 0x300
	v_cndmask_b32_e64 v8, 0, 1, s[16:17]
	v_cmp_ge_u32_e64 s[16:17], v7, v9
	s_add_u32 s80, s74, s65
	v_mov_b32_e32 v25, 0
	v_cndmask_b32_e64 v7, 0, 1, s[16:17]
; DI unsigned pkbf(float a, float b) { f32x2 v = {a, b}; bfx2 r = __builtin_convertvector(v, bfx2); return __builtin_bit_cast(unsigned, r); }
; DI void phase_gla_prep(const Params& P, int l, int bid, int nb, LAS unsigned char* lds) {
;     const int tid = threadIdx.x, wid = tid >> 6, lane = tid & 63, dpl = lane & 7, rg = lane >> 3, r32 = lane & 31, hi = lane >> 5;
;     const bf16_t* PG = (const bf16_t*)(P.ws + WS_PG); const float* LR = (const float*)(P.ws + WS_LR);
;     const int c0 = wid * 16 + dpl * 2;
;     const int p0 = (c0 & ~15) | (c0 & 3) | ((c0 & 4) << 1) | ((c0 & 8) >> 1);
;     ...
;           for (int a4 = 0; a4 < 4; ++a4) { float v[4];
; #pragma unroll
;               for (int b4 = 0; b4 < 4; ++b4) { const int j = tj * 32 + 8 * a4 + 4 * hi + b4; const bool keep = dir ? (j >= i) : (j <= i); v[b4] = keep ? acc[a4 * 4 + b4] : 0.f; }
;               u32x2 w; w.x = pkbf(v[0], v[1]); w.y = pkbf(v[2], v[3]);
;               *(u32x2*)(am + i * 128 + ((((4 * tj + a4) ^ ((i >> 1) & 7)) << 4) | (hi << 3))) = w; } }
	v_cndmask_b32_e32 v7, v7, v8, vcc
	v_and_b32_e32 v7, 1, v7
	v_cmp_eq_u32_e64 s[16:17], 1, v7
	v_bitop3_b32 v7, v15, v65, 7 bitop3:0x78
	v_lshl_or_b32 v38, v7, 4, v17
	v_or_b32_e32 v7, 8, v13
	v_cmp_le_u32_e64 s[18:19], v7, v9
	s_addc_u32 s81, s75, 0
	v_mul_u32_u24_e32 v34, 0xa00, v12
	v_cndmask_b32_e64 v8, 0, 1, s[18:19]
	v_cmp_ge_u32_e64 s[18:19], v7, v9
	v_lshlrev_b32_e32 v83, 12, v12
	v_lshlrev_b32_e32 v56, 12, v64
	v_cndmask_b32_e64 v7, 0, 1, s[18:19]
	v_cndmask_b32_e32 v7, v7, v8, vcc
	v_and_b32_e32 v7, 1, v7
	v_cmp_eq_u32_e64 s[18:19], 1, v7
	v_or_b32_e32 v7, 9, v13
	v_cmp_le_u32_e64 s[20:21], v7, v9
	v_mov_b32_e32 v57, v25
	s_movk_i32 s65, 0x1000
	v_cndmask_b32_e64 v8, 0, 1, s[20:21]
	v_cmp_ge_u32_e64 s[20:21], v7, v9
	v_lshlrev_b32_e32 v22, 4, v136
	v_mov_b32_e32 v23, v25
	v_cndmask_b32_e64 v7, 0, 1, s[20:21]
	v_cndmask_b32_e32 v7, v7, v8, vcc
	v_and_b32_e32 v7, 1, v7
	v_cmp_eq_u32_e64 s[20:21], 1, v7
	v_or_b32_e32 v7, 10, v13
	v_cmp_le_u32_e64 s[22:23], v7, v9
	v_lshl_add_u64 v[26:27], s[44:45], 0, v[22:23]
	v_and_b32_e32 v4, 0xff, v136
	v_cndmask_b32_e64 v8, 0, 1, s[22:23]
	v_cmp_ge_u32_e64 s[22:23], v7, v9
	v_add_u32_e32 v142, s70, v6
	v_lshl_add_u32 v79, v4, 1, 0
	v_cndmask_b32_e64 v7, 0, 1, s[22:23]
	v_cndmask_b32_e32 v7, v7, v8, vcc
	v_and_b32_e32 v7, 1, v7
	v_cmp_eq_u32_e64 s[22:23], 1, v7
	v_or_b32_e32 v7, 11, v13
	v_cmp_le_u32_e64 s[24:25], v7, v9
	v_lshlrev_b32_e32 v4, 7, v4
	v_mov_b32_e32 v5, v25
	v_cndmask_b32_e64 v8, 0, 1, s[24:25]
	v_cmp_ge_u32_e64 s[24:25], v7, v9
	v_lshl_add_u32 v178, v64, 7, 0
	v_lshl_add_u64 v[4:5], s[50:51], 0, v[4:5]
	v_cndmask_b32_e64 v7, 0, 1, s[24:25]
	v_cndmask_b32_e32 v7, v7, v8, vcc
	v_and_b32_e32 v7, 1, v7
	v_cmp_eq_u32_e64 s[24:25], 1, v7
	v_bitop3_b32 v7, v15, v16, 1 bitop3:0x36
	v_lshl_or_b32 v40, v7, 4, v17
	v_or_b32_e32 v7, 16, v13
	v_cmp_le_u32_e64 s[26:27], v7, v9
	v_and_b32_e32 v78, 0x7f, v136
	s_movk_i32 s64, 0x200
	v_cndmask_b32_e64 v8, 0, 1, s[26:27]
	v_cmp_ge_u32_e64 s[26:27], v7, v9
	v_lshl_add_u64 v[66:67], s[78:79], 0, v[22:23]
	v_add_u32_e32 v183, s70, v3
	v_cndmask_b32_e64 v7, 0, 1, s[26:27]
	v_cndmask_b32_e32 v7, v7, v8, vcc
	v_and_b32_e32 v7, 1, v7
	v_cmp_eq_u32_e64 s[26:27], 1, v7
	v_or_b32_e32 v7, 17, v13
	v_cmp_le_u32_e64 s[28:29], v7, v9
	v_lshlrev_b32_e32 v10, 4, v81
	v_lshl_add_u64 v[28:29], s[74:75], 0, v[24:25]
	v_cndmask_b32_e64 v8, 0, 1, s[28:29]
	v_cmp_ge_u32_e64 s[28:29], v7, v9
	v_lshlrev_b32_e32 v36, 7, v9
	v_and_b32_e32 v10, 0x3ff0, v10
	v_cndmask_b32_e64 v7, 0, 1, s[28:29]
	v_cndmask_b32_e32 v7, v7, v8, vcc
	v_and_b32_e32 v7, 1, v7
	v_cmp_eq_u32_e64 s[28:29], 1, v7
	v_or_b32_e32 v7, 18, v13
	v_cmp_le_u32_e64 s[30:31], v7, v9
	v_mov_b32_e32 v11, v25
	s_mov_b32 s77, 0
	v_cndmask_b32_e64 v8, 0, 1, s[30:31]
	v_cmp_ge_u32_e64 s[30:31], v7, v9
	v_mov_b32_e32 v31, v25
	v_mov_b32_e32 v33, v25
	v_cndmask_b32_e64 v7, 0, 1, s[30:31]
	v_cndmask_b32_e32 v7, v7, v8, vcc
	v_and_b32_e32 v7, 1, v7
	v_cmp_eq_u32_e64 s[30:31], 1, v7
	v_or_b32_e32 v7, 19, v13
	v_cmp_le_u32_e64 s[34:35], v7, v9
	v_mov_b32_e32 v35, v25
	v_mov_b32_e32 v37, v25
	v_cndmask_b32_e64 v8, 0, 1, s[34:35]
	v_cmp_ge_u32_e64 s[34:35], v7, v9
	v_mov_b32_e32 v39, v25
	v_mov_b32_e32 v41, v25
	v_cndmask_b32_e64 v7, 0, 1, s[34:35]
	v_cndmask_b32_e32 v7, v7, v8, vcc
	v_and_b32_e32 v7, 1, v7
	v_cmp_eq_u32_e64 s[34:35], 1, v7
	v_bitop3_b32 v7, v15, v16, 2 bitop3:0x36
	v_lshl_or_b32 v42, v7, 4, v17
	v_or_b32_e32 v7, 24, v13
	v_cmp_le_u32_e64 s[36:37], v7, v9
	v_mov_b32_e32 v43, v25
	v_mov_b32_e32 v45, v25
	v_cndmask_b32_e64 v8, 0, 1, s[36:37]
	v_cmp_ge_u32_e64 s[36:37], v7, v9
	v_mov_b32_e32 v47, v25
	v_mov_b32_e32 v49, v25
	v_cndmask_b32_e64 v7, 0, 1, s[36:37]
	v_cndmask_b32_e32 v7, v7, v8, vcc
	v_and_b32_e32 v7, 1, v7
	v_cmp_eq_u32_e64 s[36:37], 1, v7
	v_or_b32_e32 v7, 25, v13
	v_cmp_le_u32_e64 s[38:39], v7, v9
	v_mov_b32_e32 v51, v25
	v_mov_b32_e32 v53, v25
	v_cndmask_b32_e64 v8, 0, 1, s[38:39]
	v_cmp_ge_u32_e64 s[38:39], v7, v9
	v_mov_b32_e32 v55, v25
	v_lshl_add_u64 v[72:73], s[78:79], 0, v[10:11]
	v_cndmask_b32_e64 v7, 0, 1, s[38:39]
	v_cndmask_b32_e32 v7, v7, v8, vcc
	v_and_b32_e32 v7, 1, v7
	v_cmp_eq_u32_e64 s[38:39], 1, v7
	v_or_b32_e32 v7, 26, v13
	v_cmp_le_u32_e64 s[40:41], v7, v9
	s_mov_b32 s90, 0xbfb8aa3b
	s_mov_b32 s91, 0xa000
	v_cndmask_b32_e64 v8, 0, 1, s[40:41]
	v_cmp_ge_u32_e64 s[40:41], v7, v9
	v_add_u32_e32 v208, v79, v83
	v_mov_b32_e32 v215, 0xa000
	v_cndmask_b32_e64 v7, 0, 1, s[40:41]
	v_cndmask_b32_e32 v7, v7, v8, vcc
	v_and_b32_e32 v7, 1, v7
	v_cmp_eq_u32_e64 s[40:41], 1, v7
	v_or_b32_e32 v7, 27, v13
	v_cmp_le_u32_e64 s[42:43], v7, v9
	s_nop 1
	v_cndmask_b32_e64 v8, 0, 1, s[42:43]
	v_cmp_ge_u32_e64 s[42:43], v7, v9
	v_mov_b32_e32 v9, v25
	s_nop 0
	v_cndmask_b32_e64 v7, 0, 1, s[42:43]
; #define PP_FETCH(task_) do { const int c_ = (task_) >> 2, h_ = (task_) & 3; const size_t t0_ = (size_t)c_ * 64; \
;         n_lr = *(const f32x4*)(LR + t0_ * 32 + tid * 4); \
;         _Pragma("unroll") for (int r_ = 0; r_ < 8; ++r_) { const bf16_t* rp_ = PG + (t0_ + rg * 8 + r_) * 2048 + h_ * 128 + c0; n_q[r_] = *(const unsigned*)rp_; n_k[r_] = *(const unsigned*)(rp_ + 512); } } while (0)
; DI void phase_gla_prep(const Params& P, int l, int bid, int nb, LAS unsigned char* lds) {
;     ...
;     if (bid < 2560) PP_FETCH(bid);
;     f32x2 bbs[2] = {{0.f, 0.f}, {0.f, 0.f}};
;     for (int task = bid; task < 2560; task += nb) {
	v_cndmask_b32_e32 v7, v7, v8, vcc
	v_and_b32_e32 v7, 1, v7
	v_cmp_eq_u32_e64 s[42:43], 1, v7
	v_bitop3_b32 v7, v15, v16, 3 bitop3:0x36
	v_lshl_or_b32 v44, v7, 4, v17
	v_lshrrev_b32_e32 v7, 10, v76
	v_lshl_add_u32 v80, v7, 14, 0
	v_mul_u32_u24_e32 v46, 0xa00, v7
	v_lshrrev_b32_e32 v7, 10, v81
	v_lshl_add_u32 v82, v7, 14, 0
	v_mul_u32_u24_e32 v48, 0xa00, v7
	v_bitop3_b32 v7, v65, v12, 7 bitop3:0x6c
	v_lshlrev_b32_e32 v50, 4, v7
	v_lshrrev_b32_e32 v7, 8, v76
	v_lshlrev_b32_e32 v84, 12, v7
	v_bitop3_b32 v7, v7, v65, 7 bitop3:0x78
	v_lshlrev_b32_e32 v52, 4, v7
	v_or_b32_e32 v7, 4, v12
	v_lshlrev_b32_e32 v85, 12, v7
	v_bitop3_b32 v7, v12, v16, 4 bitop3:0x36
	v_lshl_add_u64 v[12:13], s[80:81], 0, v[24:25]
	s_ashr_i32 s80, s33, 2
	s_ashr_i32 s81, s80, 31
	s_lshl_b64 s[82:83], s[80:81], 18
	v_lshl_add_u64 v[12:13], v[12:13], 0, s[82:83]
	v_lshl_add_u64 v[12:13], v[12:13], 0, v[56:57]
	s_lshl_b64 s[80:81], s[80:81], 13
	v_add_co_u32_e32 v14, vcc, s65, v12
	s_add_u32 s44, s44, s80
	s_nop 0
	v_addc_co_u32_e32 v15, vcc, 0, v13, vcc
	s_movk_i32 s65, 0x2000
	s_addc_u32 s45, s45, s81
	v_add_co_u32_e32 v16, vcc, s65, v12
	v_lshlrev_b32_e32 v54, 4, v7
	s_nop 0
	v_addc_co_u32_e32 v17, vcc, 0, v13, vcc
	global_load_dwordx4 v[18:21], v22, s[44:45]
	global_load_dword v177, v[16:17], off offset:-4096
	global_load_dword v179, v[16:17], off
	global_load_dword v180, v[16:17], off offset:1024
	s_movk_i32 s44, 0x3000
	v_add_co_u32_e32 v16, vcc, s44, v12
	s_movk_i32 s44, 0x4000
	s_nop 0
	v_addc_co_u32_e32 v17, vcc, 0, v13, vcc
	v_add_co_u32_e32 v58, vcc, s44, v12
	s_movk_i32 s44, 0x5000
	s_nop 0
	v_addc_co_u32_e32 v59, vcc, 0, v13, vcc
	v_add_co_u32_e32 v60, vcc, s44, v12
	s_movk_i32 s44, 0x6000
	s_nop 0
	v_addc_co_u32_e32 v61, vcc, 0, v13, vcc
	v_add_co_u32_e32 v62, vcc, s44, v12
	s_movk_i32 s44, 0x7000
	s_nop 0
	v_addc_co_u32_e32 v63, vcc, 0, v13, vcc
	global_load_dword v188, v[58:59], off offset:-4096
	global_load_dword v189, v[58:59], off
	global_load_dword v190, v[58:59], off offset:1024
	global_load_dword v196, v[62:63], off offset:-4096
	global_load_dword v204, v[62:63], off
	global_load_dword v205, v[62:63], off offset:1024
	v_add_co_u32_e32 v58, vcc, s44, v12
	v_lshrrev_b32_e32 v7, 8, v81
	s_nop 0
	v_addc_co_u32_e32 v59, vcc, 0, v13, vcc
	global_load_dword v181, v[12:13], off
	global_load_dword v182, v[12:13], off offset:1024
	global_load_dword v195, v[14:15], off offset:1024
	global_load_dword v199, v[16:17], off offset:1024
	global_load_dword v212, v[60:61], off offset:1024
	global_load_dword v216, v[58:59], off
	global_load_dword v217, v[58:59], off offset:1024
	v_lshlrev_b32_e32 v12, 12, v7
	v_bitop3_b32 v7, v7, v65, 7 bitop3:0x78
	v_lshlrev_b32_e32 v58, 4, v7
	v_mov_b32_e32 v7, v25
	v_lshl_add_u64 v[60:61], s[54:55], 0, v[6:7]
	v_lshl_add_u64 v[62:63], s[58:59], 0, v[6:7]
	v_lshl_add_u64 v[6:7], s[50:51], 0, v[6:7]
	s_mov_b64 s[44:45], 0x3b670000
	v_lshl_add_u64 v[64:65], v[6:7], 0, s[44:45]
	v_lshl_add_u64 v[6:7], s[50:51], 0, v[22:23]
	s_mov_b64 s[44:45], 0x30270000
	v_lshl_add_u64 v[70:71], v[6:7], 0, s[44:45]
	s_mov_b64 s[44:45], 0x36670000
	v_lshl_add_u64 v[74:75], v[4:5], 0, s[44:45]
	v_lshlrev_b32_e32 v4, 2, v76
	s_movk_i32 s54, 0x1e00
	v_and_or_b32 v184, v4, s54, v78
	v_add_u32_e32 v185, s70, v4
	v_or_b32_e32 v4, 0x1000, v3
	v_and_or_b32 v186, v4, s54, v78
	v_add_u32_e32 v187, s70, v4
	v_mov_b32_e32 v4, s57
	v_mov_b32_e32 v5, s53
	v_cmp_gt_u32_e32 vcc, s64, v136
	v_lshlrev_b32_e32 v8, 4, v76
	s_movk_i32 s44, 0xe00
	v_cndmask_b32_e32 v77, v4, v5, vcc
	v_mov_b32_e32 v4, s56
	v_mov_b32_e32 v5, s52
	v_cndmask_b32_e32 v76, v4, v5, vcc
	v_lshlrev_b32_e32 v4, 2, v81
	v_and_or_b32 v191, v4, s54, v78
	v_add_u32_e32 v192, s70, v4
	v_add_u32_e32 v4, 0x2800, v3
	v_and_or_b32 v193, v4, s54, v78
	v_add_u32_e32 v194, s70, v4
	v_or_b32_e32 v4, 0xc00, v136
	v_and_or_b32 v23, v3, s44, v78
	v_lshlrev_b32_e32 v5, 2, v4
	v_add_u32_e32 v3, 0x3800, v3
	v_and_or_b32 v197, v5, s54, v78
	v_and_or_b32 v201, v3, s54, v78
	v_lshlrev_b32_e32 v78, 1, v2
	v_mbcnt_lo_u32_b32 v2, -1, 0
	v_and_b32_e32 v8, 0x3ff0, v8
	v_mov_b32_e32 v24, v25
	v_mbcnt_hi_u32_b32 v213, -1, v2
	v_mov_b32_e32 v2, 0x80
	v_mov_b32_e32 v59, v25
	v_lshl_add_u64 v[68:69], s[78:79], 0, v[8:9]
	v_add_u32_e32 v198, s70, v5
	v_cmp_gt_u32_e64 s[44:45], s44, v4
	v_add_u32_e32 v203, s70, v3
	s_mov_b32 s70, -1
	s_mov_b64 s[54:55], 0x800
	s_mov_b64 s[58:59], 0x29e76000
	s_mov_b64 s[78:79], 0x29e74000
	v_add_u32_e32 v206, v80, v8
	v_add_u32_e32 v207, v82, v10
	v_add_u32_e32 v209, v79, v84
	v_add_u32_e32 v210, v79, v85
	v_add_u32_e32 v211, v79, v12
	v_lshl_or_b32 v214, v213, 2, v2
	v_mov_b64_e32 v[82:83], v[24:25]
	v_mov_b64_e32 v[80:81], v[24:25]
	s_mov_b32 s80, s33
	s_branch .LBB0_898

; #define LAS __attribute__((address_space(3)))
; #define PP_FETCH(task_) do { const int c_ = (task_) >> 2, h_ = (task_) & 3; const size_t t0_ = (size_t)c_ * 64; \
;         n_lr = *(const f32x4*)(LR + t0_ * 32 + tid * 4); \
;         _Pragma("unroll") for (int r_ = 0; r_ < 8; ++r_) { const bf16_t* rp_ = PG + (t0_ + rg * 8 + r_) * 2048 + h_ * 128 + c0; n_q[r_] = *(const unsigned*)rp_; n_k[r_] = *(const unsigned*)(rp_ + 512); } } while (0)
; DI void phase_gla_prep(const Params& P, int l, int bid, int nb, LAS unsigned char* lds) {
;     ...
;         *(LAS f32x4*)(lds + PP_LR + tid * 16) = n_lr;
;         unsigned qw[8], kw[8];
; #pragma unroll
;         for (int r = 0; r < 8; ++r) { qw[r] = n_q[r]; kw[r] = n_k[r]; }
;         asm volatile("" : "+v"(qw[0]), "+v"(qw[1]), "+v"(qw[2]), "+v"(qw[3]), "+v"(qw[4]), "+v"(qw[5]), "+v"(qw[6]), "+v"(qw[7]), "+v"(kw[0]), "+v"(kw[1]), "+v"(kw[2]), "+v"(kw[3]), "+v"(kw[4]), "+v"(kw[5]), "+v"(kw[6]), "+v"(kw[7]) :: "memory");
;         __builtin_amdgcn_sched_barrier(0);
;         { const int wu = __builtin_amdgcn_readfirstlane(wid);
; #pragma unroll
;           for (int q = 0; q < 4; ++q) { const int row = wu * 8 + q * 2 + (lane >> 5);
;               __builtin_amdgcn_global_load_lds((const unsigned*)(PG + ((size_t)c * 64 + row) * 2048 + 1024 + h * 256 + (lane & 31) * 8), (LAS unsigned*)(lds + PP_V + (wu * 8 + q * 2) * 512), 16, 0, 0); } }
;         if (task + nb < 2560) PP_FETCH(task + nb);
.LBB0_902:
	v_add_u32_e32 v24, 0, v22
	ds_write_b128 v24, v[18:21]
	v_mov_b32_e32 v7, v189
	v_mov_b32_e32 v9, v199
	v_mov_b32_e32 v3, v204
	v_mov_b32_e32 v5, v212
	v_mov_b32_e32 v13, v177
	v_mov_b32_e32 v15, v182
	v_mov_b32_e32 v2, v217
	v_mov_b32_e32 v11, v188
	v_mov_b32_e32 v12, v180
	v_mov_b32_e32 v8, v196
	v_mov_b32_e32 v10, v190
	v_mov_b32_e32 v17, v181
	v_mov_b32_e32 v4, v216
	v_mov_b32_e32 v6, v205
	v_mov_b32_e32 v14, v179
	v_mov_b32_e32 v16, v195
	s_ashr_i32 s82, s80, 2
	v_readfirstlane_b32 s64, v137
	s_lshl_b32 s65, s64, 3
	s_ashr_i32 s83, s82, 31
	s_lshl_b64 s[82:83], s[82:83], 18
	v_or_b32_e32 v84, s65, v139
	s_add_u32 s82, s74, s82
	v_ashrrev_i32_e32 v85, 31, v84
	s_addc_u32 s83, s75, s83
	v_lshlrev_b64 v[84:85], 12, v[84:85]
	v_lshl_add_u64 v[84:85], s[82:83], 0, v[84:85]
	s_lshl_b32 s76, s71, 9
	v_lshl_add_u64 v[84:85], v[84:85], 0, s[76:77]
	v_mov_b32_e32 v79, v25
	s_lshl_b32 s64, s64, 12
	v_lshl_add_u64 v[84:85], v[84:85], 0, v[78:79]
	s_add_i32 s64, s64, 0
	v_lshl_add_u64 v[84:85], v[84:85], 0, s[54:55]
	s_add_i32 m0, s64, 0x2000
	s_or_b32 s64, s65, 2
	global_load_lds_dwordx4 v[84:85], off
	v_or_b32_e32 v84, s64, v139
	v_ashrrev_i32_e32 v85, 31, v84
	v_lshlrev_b64 v[84:85], 12, v[84:85]
	v_lshl_add_u64 v[84:85], s[82:83], 0, v[84:85]
	v_lshl_add_u64 v[84:85], v[84:85], 0, s[76:77]
	s_lshl_b32 s64, s64, 9
	v_lshl_add_u64 v[84:85], v[84:85], 0, v[78:79]
	s_add_i32 s64, s64, 0
	v_lshl_add_u64 v[84:85], v[84:85], 0, s[54:55]
	s_add_i32 m0, s64, 0x2000
	s_or_b32 s64, s65, 4
	global_load_lds_dwordx4 v[84:85], off
	v_or_b32_e32 v84, s64, v139
	v_ashrrev_i32_e32 v85, 31, v84
	v_lshlrev_b64 v[84:85], 12, v[84:85]
	v_lshl_add_u64 v[84:85], s[82:83], 0, v[84:85]
	v_lshl_add_u64 v[84:85], v[84:85], 0, s[76:77]
	s_lshl_b32 s64, s64, 9
	v_lshl_add_u64 v[84:85], v[84:85], 0, v[78:79]
	s_add_i32 s64, s64, 0
	v_lshl_add_u64 v[84:85], v[84:85], 0, s[54:55]
	s_add_i32 m0, s64, 0x2000
	s_or_b32 s64, s65, 6
	global_load_lds_dwordx4 v[84:85], off
	v_or_b32_e32 v84, s64, v139
	v_ashrrev_i32_e32 v85, 31, v84
	v_lshlrev_b64 v[84:85], 12, v[84:85]
	v_lshl_add_u64 v[84:85], s[82:83], 0, v[84:85]
	v_lshl_add_u64 v[84:85], v[84:85], 0, s[76:77]
	s_lshl_b32 s64, s64, 9
	v_lshl_add_u64 v[84:85], v[84:85], 0, v[78:79]
	s_add_i32 s64, s64, 0
	v_lshl_add_u64 v[84:85], v[84:85], 0, s[54:55]
	s_add_i32 m0, s64, 0x2000
	s_add_i32 s71, s80, s94
	global_load_lds_dwordx4 v[84:85], off
	s_cmpk_gt_i32 s71, 0x9ff
	s_cselect_b32 s98, 0xa00, 0
	s_sub_i32 s71, s71, s98
	s_cmp_eq_u32 s71, s101
	s_cselect_b64 s[82:83], -1, 0
	s_and_b64 vcc, exec, s[82:83]
	s_cbranch_vccnz .LBB0_904
	s_ashr_i32 s84, s71, 2
	s_lshl_b32 s64, s71, 8
	s_ashr_i32 s85, s84, 31
	s_and_b32 s76, s64, 0x300
	s_lshl_b64 s[86:87], s[84:85], 13
	v_lshl_add_u64 v[20:21], v[28:29], 0, s[76:77]
	s_lshl_b64 s[84:85], s[84:85], 18
	v_lshl_add_u64 v[20:21], v[20:21], 0, s[84:85]
	v_lshl_add_u64 v[84:85], v[20:21], 0, v[56:57]
	v_add_co_u32_e32 v86, vcc, 0x1000, v84
	v_lshl_add_u64 v[18:19], v[26:27], 0, s[86:87]
	s_nop 0
	v_addc_co_u32_e32 v87, vcc, 0, v85, vcc
	v_add_co_u32_e32 v88, vcc, 0x2000, v84
	global_load_dwordx4 v[18:21], v[18:19], off
	s_nop 0
	global_load_dword v181, v[84:85], off
	global_load_dword v182, v[84:85], off offset:1024
	global_load_dword v177, v[86:87], off
	v_addc_co_u32_e32 v89, vcc, 0, v85, vcc
	v_add_co_u32_e32 v90, vcc, 0x3000, v84
	s_nop 1
	v_addc_co_u32_e32 v91, vcc, 0, v85, vcc
	v_add_co_u32_e32 v92, vcc, 0x4000, v84
	s_nop 1
	v_addc_co_u32_e32 v93, vcc, 0, v85, vcc
	v_add_co_u32_e32 v94, vcc, 0x5000, v84
	s_nop 1
	v_addc_co_u32_e32 v95, vcc, 0, v85, vcc
	global_load_dword v195, v[86:87], off offset:1024
	global_load_dword v179, v[88:89], off
	global_load_dword v180, v[88:89], off offset:1024
	global_load_dword v188, v[90:91], off
	global_load_dword v199, v[90:91], off offset:1024
	global_load_dword v189, v[92:93], off
	global_load_dword v190, v[92:93], off offset:1024
	global_load_dword v196, v[94:95], off
	v_add_co_u32_e32 v86, vcc, 0x6000, v84
	s_nop 1
	v_addc_co_u32_e32 v87, vcc, 0, v85, vcc
	v_add_co_u32_e32 v84, vcc, 0x7000, v84
	s_nop 1
	v_addc_co_u32_e32 v85, vcc, 0, v85, vcc
	global_load_dword v212, v[94:95], off offset:1024
	global_load_dword v204, v[86:87], off
	global_load_dword v205, v[86:87], off offset:1024
	global_load_dword v216, v[84:85], off
	global_load_dword v217, v[84:85], off offset:1024

; __device__ __forceinline__ unsigned xb_ld(unsigned* p)              { return __hip_atomic_load(p, __ATOMIC_RELAXED, __HIP_MEMORY_SCOPE_AGENT); }
; __device__ __forceinline__ void xcd_barrier_complete(unsigned* bar, unsigned x, unsigned& nloc, unsigned& nx) {
;     const unsigned G = gridDim.x * gridDim.y * gridDim.z;
;     unsigned sum, cnt, mine, sp = 0u;
;     for (;;) {
;         sum = 0u; cnt = 0u; mine = 0u;
; #pragma unroll
;         for (unsigned j = 0; j < 16; ++j) { const unsigned c = xb_ld(&bar[XB_XCNT(j)]); sum += c; cnt += (c > 0u) ? 1u : 0u; mine = (j == x) ? c : mine; }
; __device__ __forceinline__ void xcd_barrier(const XcdBarrier& b) {
;     ...
;     if (threadIdx.x == 0) {
;         unsigned* bar = b.bar;
;         __builtin_amdgcn_s_waitcnt(0);
;         unsigned nloc = b.st[0], nx = b.st[1];
;         if (nloc == 0u) { xcd_barrier_complete(bar, b.x, nloc, nx); b.st[0] = nloc; b.st[1] = nx; }
.LBB0_912:
	s_mov_b32 s33, s99
	s_cmp_lt_i32 s73, 10
	s_cbranch_scc1 .LBB0_962
	s_waitcnt vmcnt(0)
	v_cmp_eq_u32_e32 vcc, 0, v136
	s_waitcnt vmcnt(0) lgkmcnt(0)
	s_barrier
	s_and_saveexec_b64 s[0:1], vcc
	s_cbranch_execz .LBB0_961
	s_add_i32 s2, 0, 0x26000
	v_mov_b32_e32 v2, s2
	s_waitcnt vmcnt(0) expcnt(0) lgkmcnt(0)
	ds_read_b32 v4, v2
	s_add_i32 s2, 0, 0x26004
	v_mov_b32_e32 v2, s2
	ds_read_b32 v2, v2
	s_waitcnt lgkmcnt(1)
	v_cmp_ne_u32_e32 vcc, 0, v4
	s_cbranch_vccnz .LBB0_929
	v_readlane_b32 s2, v254, 4
	v_readlane_b32 s3, v254, 5
	s_load_dwordx2 s[6:7], s[2:3], 0x4
	s_add_u32 s2, s50, 0x29e6c200
	s_addc_u32 s3, s51, 0
	s_add_u32 s4, s50, 0x29e6c400
	s_addc_u32 s5, s51, 0
	s_waitcnt lgkmcnt(0)
	s_mul_i32 s44, s6, s94
	s_add_u32 s6, s50, 0x29e6c500
	s_mul_i32 s44, s44, s7
	s_addc_u32 s7, s51, 0
	s_add_u32 s8, s50, 0x29e6c600
	s_addc_u32 s9, s51, 0
	s_add_u32 s10, s50, 0x29e6c700
	s_addc_u32 s11, s51, 0
	s_add_u32 s12, s50, 0x29e6c800
	s_addc_u32 s13, s51, 0
	s_add_u32 s14, s50, 0x29e6c900
	s_addc_u32 s15, s51, 0
	s_add_u32 s16, s50, 0x29e6ca00
	s_addc_u32 s17, s51, 0
	s_add_u32 s18, s50, 0x29e6cb00
	s_addc_u32 s19, s51, 0
	s_add_u32 s20, s50, 0x29e6cc00
	s_addc_u32 s21, s51, 0
	s_add_u32 s22, s50, 0x29e6cd00
	s_addc_u32 s23, s51, 0
	s_add_u32 s24, s50, 0x29e6ce00
	s_addc_u32 s25, s51, 0
	s_add_u32 s26, s50, 0x29e6cf00
	s_addc_u32 s27, s51, 0
	s_add_u32 s28, s50, 0x29e6d000
	s_addc_u32 s29, s51, 0
	s_add_u32 s30, s50, 0x29e6d100
	s_addc_u32 s31, s51, 0
	s_add_u32 s34, s50, 0x29e6d200
	s_addc_u32 s35, s51, 0
	s_add_u32 s36, s50, 0x29e6d300
	s_addc_u32 s37, s51, 0
	s_mov_b32 s45, 1
	v_mov_b32_e32 v18, 0
	s_branch .LBB0_917
